# in-projection GEMM: per-tile row sum-of-squares records prefetched to LDS by LDS-DMA; epilogue reads them from LDS
# speedup vs baseline: 1.0450x; 1.0059x over previous
; template <class Epi>
; __device__ __forceinline__ void gemm_phase(LAS unsigned char* lds, const Gemm g, const Epi& E) {
;     ...
; #pragma unroll
;         for (int a = 0; a < 2; ++a)
; #pragma unroll
;             for (int b = 0; b < 2; ++b)
; #pragma unroll
;                 for (int m = 0; m < 4; ++m)
; #pragma unroll
;                     for (int n = 0; n < 2; ++n) acc[a][b][m][n] = (f32x4){0.f, 0.f, 0.f, 0.f};
;         cur = nxt; cA = nA; cB = nB; ++ui;
;     __device__ __forceinline__ void operator()(AccRef acc, const Unit& u, int wr, int wc, int fr, int fq) const {
;     ...
;                 const float rs = rsqrtf(ssq_sum<4>(ssqx + (size_t)row * 4) * (1.0f / DM) + EPS);
.LBB0_157:
	s_andn2_b64 vcc, exec, s[22:23]
	s_cbranch_vccnz .LBB0_160
	s_and_b64 vcc, exec, s[82:83]
	s_cbranch_vccnz .Lin_ssq_skip
	v_lshl_add_u32 v148, s19, 8, v208
	v_mov_b32_e32 v149, 0
	v_subrev_u32_e32 v148, 0x100, v148
	v_readfirstlane_b32 s35, v208
	v_lshl_add_u64 v[148:149], v[148:149], 4, s[64:65]
	s_nop 1
	s_lshl_b32 s35, s35, 4
	s_add_i32 s35, s35, 0x20400
	s_mov_b32 m0, s35
	s_nop 0
	global_load_lds_dwordx4 v[148:149], off
.Lin_ssq_skip:
	s_add_u32 s16, s16, 0x80
	s_addc_u32 s17, s17, 0
	s_add_u32 s20, s44, 0x100
	s_addc_u32 s21, s45, 0
	s_mov_b32 s35, 0
	v_mov_b64_e32 v[2:3], 0
	v_mov_b64_e32 v[4:5], 0
	v_mov_b64_e32 v[6:7], 0
	v_mov_b64_e32 v[8:9], 0
	v_mov_b64_e32 v[10:11], 0
	v_mov_b64_e32 v[12:13], 0
	v_mov_b64_e32 v[14:15], 0
	v_mov_b64_e32 v[16:17], 0
	v_mov_b64_e32 v[18:19], 0
	v_mov_b64_e32 v[20:21], 0
	v_mov_b64_e32 v[22:23], 0
	v_mov_b64_e32 v[24:25], 0
	v_mov_b64_e32 v[26:27], 0
	v_mov_b64_e32 v[28:29], 0
	v_mov_b64_e32 v[30:31], 0
	v_mov_b64_e32 v[32:33], 0
	v_mov_b64_e32 v[34:35], 0
	v_mov_b64_e32 v[36:37], 0
	v_mov_b64_e32 v[38:39], 0
	v_mov_b64_e32 v[40:41], 0
	v_mov_b64_e32 v[42:43], 0
	v_mov_b64_e32 v[44:45], 0
	v_mov_b64_e32 v[46:47], 0
	v_mov_b64_e32 v[48:49], 0
	v_mov_b64_e32 v[50:51], 0
	v_mov_b64_e32 v[52:53], 0
	v_mov_b64_e32 v[54:55], 0
	v_mov_b64_e32 v[56:57], 0
	v_mov_b64_e32 v[58:59], 0
	v_mov_b64_e32 v[60:61], 0
	v_mov_b64_e32 v[62:63], 0
	v_mov_b64_e32 v[64:65], 0
	v_mov_b64_e32 v[66:67], 0
	v_mov_b64_e32 v[68:69], 0
	v_mov_b64_e32 v[70:71], 0
	v_mov_b64_e32 v[72:73], 0
	v_mov_b64_e32 v[74:75], 0
	v_mov_b64_e32 v[76:77], 0
	v_mov_b64_e32 v[78:79], 0
	v_mov_b64_e32 v[80:81], 0
	v_mov_b64_e32 v[82:83], 0
	v_mov_b64_e32 v[84:85], 0
	v_mov_b64_e32 v[86:87], 0
	v_mov_b64_e32 v[88:89], 0
	v_mov_b64_e32 v[90:91], 0
	v_mov_b64_e32 v[92:93], 0
	v_mov_b64_e32 v[94:95], 0
	v_mov_b64_e32 v[96:97], 0
	v_mov_b64_e32 v[98:99], 0
	v_mov_b64_e32 v[100:101], 0
	v_mov_b64_e32 v[102:103], 0
	v_mov_b64_e32 v[104:105], 0
	v_mov_b64_e32 v[106:107], 0
	v_mov_b64_e32 v[108:109], 0
	v_mov_b64_e32 v[110:111], 0
	v_mov_b64_e32 v[112:113], 0
	v_mov_b64_e32 v[114:115], 0
	v_mov_b64_e32 v[116:117], 0
	v_mov_b64_e32 v[118:119], 0
	v_mov_b64_e32 v[120:121], 0
	v_mov_b64_e32 v[122:123], 0
	v_mov_b64_e32 v[124:125], 0
	v_mov_b64_e32 v[126:127], 0
	v_mov_b64_e32 v[128:129], 0

;     __device__ __forceinline__ void operator()(AccRef acc, const Unit& u, int wr, int wc, int fr, int fq) const {
;     ...
;                 const int row = row0 + ai * 128 + m * 16;
;                 const float rs = rsqrtf(ssq_sum<4>(ssqx + (size_t)row * 4) * (1.0f / DM) + EPS);
;                 bf16_t* rowp = O + (size_t)row * NPROJ + col0;
; #pragma unroll
;                 for (int bj = 0; bj < 2; ++bj) {
;                     f32x4 v0 = acc[ai][bj][m][0] * rs, v1 = acc[ai][bj][m][1] * rs;
;                     if (u.pn == 6 || (u.pn == 7 && bj == 0)) {
;                         float s = (v0[0] * v0[0] + v0[1] * v0[1]) + (v0[2] * v0[2] + v0[3] * v0[3]) + (v1[0] * v1[0] + v1[1] * v1[1]) + (v1[2] * v1[2] + v1[3] * v1[3]);
;                         s += __shfl_xor(s, 16); s += __shfl_xor(s, 32);
;                         if (fq == 0) { if (u.pn == 6) ssqq[(size_t)row * 8 + bj * 4 + wc] = s; else ssqkv[(size_t)row * 4 + wc] = s; }
;                     }
.LBB0_162:
	v_lshl_add_u32 v148, s19, 8, v164
	v_ashrrev_i32_e32 v149, 31, v148
	v_and_b32_e32 v150, 0xff, v148
	v_lshlrev_b32_e32 v150, 4, v150
	v_add_u32_e32 v150, 0x21400, v150
	ds_read_b128 v[150:153], v150
	s_cmp_eq_u32 s18, 6
	s_cselect_b64 s[42:43], -1, 0
	s_cmp_lg_u32 s18, 6
	s_cselect_b64 s[46:47], -1, 0
	s_and_b32 s19, s18, -2
	s_cmp_eq_u32 s19, 6
	v_lshlrev_b64 v[162:163], 5, v[148:149]
	s_cselect_b64 s[16:17], -1, 0
	s_cmp_lg_u32 s19, 6
	s_waitcnt lgkmcnt(0)
	v_mov_b32_e32 v154, v151
	v_mov_b32_e32 v155, v152
	v_mov_b32_e32 v151, v153
	v_pk_add_f32 v[150:151], v[154:155], v[150:151]
	s_nop 0
	v_add_f32_e32 v0, v150, v151
	v_add_f32_e32 v0, 0, v0
	v_fmamk_f32 v0, v0, 0x3a800000, v212
	v_cmp_gt_f32_e32 vcc, s69, v0
	v_mul_f32_e32 v150, 0x4b800000, v0
	s_nop 0
	v_cndmask_b32_e32 v0, v0, v150, vcc
	v_rsq_f32_e32 v0, v0
	s_nop 0
	v_mul_f32_e32 v150, 0x45800000, v0
	v_cndmask_b32_e32 v156, v0, v150, vcc
	v_pk_mul_f32 v[124:125], v[124:125], v[156:157] op_sel_hi:[1,0]
	v_pk_mul_f32 v[154:155], v[122:123], v[156:157] op_sel_hi:[1,0]
	v_pk_mul_f32 v[122:123], v[128:129], v[156:157] op_sel_hi:[1,0]
	v_pk_mul_f32 v[126:127], v[126:127], v[156:157] op_sel_hi:[1,0]
	s_cbranch_scc1 .LBB0_166
	v_mul_f32_e32 v0, v155, v155
	v_mul_f32_e32 v128, v125, v125
	v_fmac_f32_e32 v0, v154, v154
	v_fmac_f32_e32 v128, v124, v124
	v_add_f32_e32 v0, v0, v128
	v_mul_f32_e32 v128, v127, v127
	v_fmac_f32_e32 v128, v126, v126
	v_add_f32_e32 v0, v128, v0
	v_mul_f32_e32 v128, v123, v123
	v_fmac_f32_e32 v128, v122, v122
	v_and_b32_e32 v129, 64, v213
	v_add_f32_e32 v0, v128, v0
	v_xor_b32_e32 v128, 16, v213
	v_add_u32_e32 v129, 64, v129
	v_cmp_lt_i32_e32 vcc, v128, v129
	s_nop 1
	v_cndmask_b32_e32 v128, v213, v128, vcc
	v_lshlrev_b32_e32 v128, 2, v128
	ds_bpermute_b32 v128, v128, v0
	s_waitcnt lgkmcnt(0)
	v_add_f32_e32 v0, v0, v128
	v_xor_b32_e32 v128, 32, v213
	v_cmp_lt_i32_e32 vcc, v128, v129
	s_nop 1
	v_cndmask_b32_e32 v128, v213, v128, vcc
	v_lshlrev_b32_e32 v128, 2, v128
	ds_bpermute_b32 v128, v128, v0
	s_and_saveexec_b64 s[20:21], s[38:39]
	s_cbranch_execz .LBB0_165
	v_lshlrev_b64 v[150:151], 2, v[148:149]
	v_lshl_add_u64 v[152:153], s[78:79], 0, v[162:163]
	v_lshl_add_u64 v[150:151], v[150:151], 2, s[88:89]
	v_cndmask_b32_e64 v151, v151, v153, s[42:43]
	v_cndmask_b32_e64 v150, v150, v152, s[42:43]
	s_lshl_b32 s72, s4, 2
	v_lshl_add_u64 v[150:151], v[150:151], 0, s[72:73]
	s_waitcnt lgkmcnt(0)
	v_add_f32_e32 v0, v0, v128
	global_store_dword v[150:151], v0, off

; __device__ __forceinline__ unsigned cvtpk(float lo, float hi) { f32x2 v = {lo, hi}; bf16x2_t b = __builtin_convertvector(v, bf16x2_t); return __builtin_bit_cast(unsigned, b); }
;     __device__ __forceinline__ void operator()(AccRef acc, const Unit& u, int wr, int wc, int fr, int fq) const {
;     ...
;                 const int row = row0 + ai * 128 + m * 16;
;                 const float rs = rsqrtf(ssq_sum<4>(ssqx + (size_t)row * 4) * (1.0f / DM) + EPS);
;                 bf16_t* rowp = O + (size_t)row * NPROJ + col0;
; #pragma unroll
;                 for (int bj = 0; bj < 2; ++bj) {
;                     f32x4 v0 = acc[ai][bj][m][0] * rs, v1 = acc[ai][bj][m][1] * rs;
;                     if (u.pn == 6 || (u.pn == 7 && bj == 0)) {
;                         float s = (v0[0] * v0[0] + v0[1] * v0[1]) + (v0[2] * v0[2] + v0[3] * v0[3]) + (v1[0] * v1[0] + v1[1] * v1[1]) + (v1[2] * v1[2] + v1[3] * v1[3]);
;                         s += __shfl_xor(s, 16); s += __shfl_xor(s, 32);
;                         if (fq == 0) { if (u.pn == 6) ssqq[(size_t)row * 8 + bj * 4 + wc] = s; else ssqkv[(size_t)row * 4 + wc] = s; }
;                     }
;                     if (u.pn == 7 && bj == 1 && wc == 0) { const int pos = row & (SEQ - 1); rope8(v0, v1, cost + pos * 16, sint + pos * 16, fq); }
;                     u32x4 w; w.x = cvtpk(v0[0], v0[1]); w.y = cvtpk(v0[2], v0[3]); w.z = cvtpk(v1[0], v1[1]); w.w = cvtpk(v1[2], v1[3]);
;                     st16_wt(rowp + bj * 128, w);
.LBB0_174:
	s_waitcnt lgkmcnt(0)
	v_cvt_pk_bf16_f32 v114, v160, v161
	v_cvt_pk_bf16_f32 v115, v154, v155
	v_cvt_pk_bf16_f32 v116, v156, v157
	v_cvt_pk_bf16_f32 v117, v158, v159
	v_or_b32_e32 v124, 16, v148
	global_store_dwordx4 v[152:153], v[114:117], off offset:256
	v_ashrrev_i32_e32 v125, 31, v124
	v_cndmask_b32_e64 v0, 0, 1, s[16:17]
	v_and_b32_e32 v114, 0xff, v124
	v_lshlrev_b32_e32 v114, 4, v114
	v_add_u32_e32 v114, 0x21400, v114
	ds_read_b128 v[114:117], v114
	v_cmp_ne_u32_e64 s[48:49], 1, v0
	v_lshlrev_b64 v[126:127], 5, v[124:125]
	s_andn2_b64 vcc, exec, s[16:17]
	s_waitcnt lgkmcnt(0)
	v_mov_b32_e32 v118, v115
	v_mov_b32_e32 v119, v116
	v_mov_b32_e32 v115, v117
	v_pk_add_f32 v[114:115], v[118:119], v[114:115]
	s_nop 0
	v_add_f32_e32 v114, v114, v115
	v_add_f32_e32 v114, 0, v114
	v_fmamk_f32 v114, v114, 0x3a800000, v212
	v_mul_f32_e32 v115, 0x4b800000, v114
	v_cmp_gt_f32_e64 s[50:51], s69, v114
	s_nop 1
	v_cndmask_b32_e64 v114, v114, v115, s[50:51]
	v_rsq_f32_e32 v114, v114
	s_nop 0
	v_mul_f32_e32 v0, 0x45800000, v114
	v_cndmask_b32_e64 v118, v114, v0, s[50:51]
	v_pk_mul_f32 v[112:113], v[112:113], v[118:119] op_sel_hi:[1,0]
	v_pk_mul_f32 v[110:111], v[110:111], v[118:119] op_sel_hi:[1,0]
	v_pk_mul_f32 v[108:109], v[108:109], v[118:119] op_sel_hi:[1,0]
	v_pk_mul_f32 v[106:107], v[106:107], v[118:119] op_sel_hi:[1,0]
	s_cbranch_vccnz .LBB0_178
	v_mul_f32_e32 v0, v111, v111
	v_mul_f32_e32 v114, v113, v113
	v_fmac_f32_e32 v0, v110, v110
	v_fmac_f32_e32 v114, v112, v112
	v_add_f32_e32 v0, v0, v114
	v_mul_f32_e32 v114, v107, v107
	v_fmac_f32_e32 v114, v106, v106
	v_add_f32_e32 v0, v114, v0
	v_mul_f32_e32 v114, v109, v109
	v_fmac_f32_e32 v114, v108, v108
	v_and_b32_e32 v115, 64, v213
	v_add_f32_e32 v0, v114, v0
	v_xor_b32_e32 v114, 16, v213
	v_add_u32_e32 v115, 64, v115
	v_cmp_lt_i32_e32 vcc, v114, v115
	s_nop 1
	v_cndmask_b32_e32 v114, v213, v114, vcc
	v_lshlrev_b32_e32 v114, 2, v114
	ds_bpermute_b32 v114, v114, v0
	s_waitcnt lgkmcnt(0)
	v_add_f32_e32 v0, v0, v114
	v_xor_b32_e32 v114, 32, v213
	v_cmp_lt_i32_e32 vcc, v114, v115
	s_nop 1
	v_cndmask_b32_e32 v114, v213, v114, vcc
	v_lshlrev_b32_e32 v114, 2, v114
	ds_bpermute_b32 v114, v114, v0
	s_and_saveexec_b64 s[16:17], s[38:39]
	s_cbranch_execz .LBB0_177
	v_lshlrev_b64 v[116:117], 2, v[124:125]
	v_lshl_add_u64 v[120:121], s[78:79], 0, v[126:127]
	v_lshl_add_u64 v[116:117], v[116:117], 2, s[88:89]
	v_cndmask_b32_e64 v117, v117, v121, s[42:43]
	v_cndmask_b32_e64 v116, v116, v120, s[42:43]
	s_lshl_b32 s72, s4, 2
	v_lshl_add_u64 v[116:117], v[116:117], 0, s[72:73]
	s_waitcnt lgkmcnt(0)
	v_add_f32_e32 v0, v0, v114
	global_store_dword v[116:117], v0, off

; __device__ __forceinline__ unsigned cvtpk(float lo, float hi) { f32x2 v = {lo, hi}; bf16x2_t b = __builtin_convertvector(v, bf16x2_t); return __builtin_bit_cast(unsigned, b); }
;     __device__ __forceinline__ void operator()(AccRef acc, const Unit& u, int wr, int wc, int fr, int fq) const {
;     ...
;                 const int row = row0 + ai * 128 + m * 16;
;                 const float rs = rsqrtf(ssq_sum<4>(ssqx + (size_t)row * 4) * (1.0f / DM) + EPS);
;                 bf16_t* rowp = O + (size_t)row * NPROJ + col0;
; #pragma unroll
;                 for (int bj = 0; bj < 2; ++bj) {
;                     f32x4 v0 = acc[ai][bj][m][0] * rs, v1 = acc[ai][bj][m][1] * rs;
;                     if (u.pn == 6 || (u.pn == 7 && bj == 0)) {
;                         float s = (v0[0] * v0[0] + v0[1] * v0[1]) + (v0[2] * v0[2] + v0[3] * v0[3]) + (v1[0] * v1[0] + v1[1] * v1[1]) + (v1[2] * v1[2] + v1[3] * v1[3]);
;                         s += __shfl_xor(s, 16); s += __shfl_xor(s, 32);
;                         if (fq == 0) { if (u.pn == 6) ssqq[(size_t)row * 8 + bj * 4 + wc] = s; else ssqkv[(size_t)row * 4 + wc] = s; }
;                     }
;                     if (u.pn == 7 && bj == 1 && wc == 0) { const int pos = row & (SEQ - 1); rope8(v0, v1, cost + pos * 16, sint + pos * 16, fq); }
;                     u32x4 w; w.x = cvtpk(v0[0], v0[1]); w.y = cvtpk(v0[2], v0[3]); w.z = cvtpk(v1[0], v1[1]); w.w = cvtpk(v1[2], v1[3]);
;                     st16_wt(rowp + bj * 128, w);
.LBB0_182:
	s_waitcnt lgkmcnt(0)
	v_cvt_pk_bf16_f32 v98, v122, v123
	v_cvt_pk_bf16_f32 v99, v116, v117
	v_cvt_pk_bf16_f32 v100, v118, v119
	v_cvt_pk_bf16_f32 v101, v120, v121
	v_or_b32_e32 v108, 32, v148
	global_store_dwordx4 v[114:115], v[98:101], off offset:256
	v_ashrrev_i32_e32 v109, 31, v108
	s_and_b64 vcc, exec, s[48:49]
	v_and_b32_e32 v98, 0xff, v108
	v_lshlrev_b32_e32 v98, 4, v98
	v_add_u32_e32 v98, 0x21400, v98
	ds_read_b128 v[98:101], v98
	v_lshlrev_b64 v[110:111], 5, v[108:109]
	s_waitcnt lgkmcnt(0)
	v_mov_b32_e32 v102, v99
	v_mov_b32_e32 v103, v100
	v_mov_b32_e32 v99, v101
	v_pk_add_f32 v[98:99], v[102:103], v[98:99]
	s_nop 0
	v_add_f32_e32 v0, v98, v99
	v_add_f32_e32 v0, 0, v0
	v_fmamk_f32 v0, v0, 0x3a800000, v212
	v_mul_f32_e32 v98, 0x4b800000, v0
	v_cmp_gt_f32_e64 s[50:51], s69, v0
	s_nop 1
	v_cndmask_b32_e64 v0, v0, v98, s[50:51]
	v_rsq_f32_e32 v0, v0
	s_nop 0
	v_mul_f32_e32 v98, 0x45800000, v0
	v_cndmask_b32_e64 v102, v0, v98, s[50:51]
	v_pk_mul_f32 v[96:97], v[96:97], v[102:103] op_sel_hi:[1,0]
	v_pk_mul_f32 v[94:95], v[94:95], v[102:103] op_sel_hi:[1,0]
	v_pk_mul_f32 v[92:93], v[92:93], v[102:103] op_sel_hi:[1,0]
	v_pk_mul_f32 v[90:91], v[90:91], v[102:103] op_sel_hi:[1,0]
	s_cbranch_vccnz .LBB0_186
	v_mul_f32_e32 v0, v95, v95
	v_mul_f32_e32 v98, v97, v97
	v_fmac_f32_e32 v0, v94, v94
	v_fmac_f32_e32 v98, v96, v96
	v_add_f32_e32 v0, v0, v98
	v_mul_f32_e32 v98, v91, v91
	v_fmac_f32_e32 v98, v90, v90
	v_add_f32_e32 v0, v98, v0
	v_mul_f32_e32 v98, v93, v93
	v_fmac_f32_e32 v98, v92, v92
	v_and_b32_e32 v99, 64, v213
	v_add_f32_e32 v0, v98, v0
	v_xor_b32_e32 v98, 16, v213
	v_add_u32_e32 v99, 64, v99
	v_cmp_lt_i32_e32 vcc, v98, v99
	s_nop 1
	v_cndmask_b32_e32 v98, v213, v98, vcc
	v_lshlrev_b32_e32 v98, 2, v98
	ds_bpermute_b32 v98, v98, v0
	s_waitcnt lgkmcnt(0)
	v_add_f32_e32 v0, v0, v98
	v_xor_b32_e32 v98, 32, v213
	v_cmp_lt_i32_e32 vcc, v98, v99
	s_nop 1
	v_cndmask_b32_e32 v98, v213, v98, vcc
	v_lshlrev_b32_e32 v98, 2, v98
	ds_bpermute_b32 v98, v98, v0
	s_and_saveexec_b64 s[16:17], s[38:39]
	s_cbranch_execz .LBB0_185
	v_lshlrev_b64 v[100:101], 2, v[108:109]
	v_lshl_add_u64 v[104:105], s[78:79], 0, v[110:111]
	v_lshl_add_u64 v[100:101], v[100:101], 2, s[88:89]
	v_cndmask_b32_e64 v101, v101, v105, s[42:43]
	v_cndmask_b32_e64 v100, v100, v104, s[42:43]
	s_lshl_b32 s72, s4, 2
	v_lshl_add_u64 v[100:101], v[100:101], 0, s[72:73]
	s_waitcnt lgkmcnt(0)
	v_add_f32_e32 v0, v0, v98
	global_store_dword v[100:101], v0, off

; __device__ __forceinline__ unsigned cvtpk(float lo, float hi) { f32x2 v = {lo, hi}; bf16x2_t b = __builtin_convertvector(v, bf16x2_t); return __builtin_bit_cast(unsigned, b); }
;     __device__ __forceinline__ void operator()(AccRef acc, const Unit& u, int wr, int wc, int fr, int fq) const {
;     ...
;                 const int row = row0 + ai * 128 + m * 16;
;                 const float rs = rsqrtf(ssq_sum<4>(ssqx + (size_t)row * 4) * (1.0f / DM) + EPS);
;                 bf16_t* rowp = O + (size_t)row * NPROJ + col0;
; #pragma unroll
;                 for (int bj = 0; bj < 2; ++bj) {
;                     f32x4 v0 = acc[ai][bj][m][0] * rs, v1 = acc[ai][bj][m][1] * rs;
;                     if (u.pn == 6 || (u.pn == 7 && bj == 0)) {
;                         float s = (v0[0] * v0[0] + v0[1] * v0[1]) + (v0[2] * v0[2] + v0[3] * v0[3]) + (v1[0] * v1[0] + v1[1] * v1[1]) + (v1[2] * v1[2] + v1[3] * v1[3]);
;                         s += __shfl_xor(s, 16); s += __shfl_xor(s, 32);
;                         if (fq == 0) { if (u.pn == 6) ssqq[(size_t)row * 8 + bj * 4 + wc] = s; else ssqkv[(size_t)row * 4 + wc] = s; }
;                     }
;                     if (u.pn == 7 && bj == 1 && wc == 0) { const int pos = row & (SEQ - 1); rope8(v0, v1, cost + pos * 16, sint + pos * 16, fq); }
;                     u32x4 w; w.x = cvtpk(v0[0], v0[1]); w.y = cvtpk(v0[2], v0[3]); w.z = cvtpk(v1[0], v1[1]); w.w = cvtpk(v1[2], v1[3]);
;                     st16_wt(rowp + bj * 128, w);
.LBB0_190:
	s_waitcnt lgkmcnt(0)
	v_cvt_pk_bf16_f32 v82, v106, v107
	v_cvt_pk_bf16_f32 v83, v100, v101
	v_cvt_pk_bf16_f32 v84, v102, v103
	v_cvt_pk_bf16_f32 v85, v104, v105
	v_or_b32_e32 v92, 48, v148
	global_store_dwordx4 v[98:99], v[82:85], off offset:256
	v_ashrrev_i32_e32 v93, 31, v92
	s_and_b64 vcc, exec, s[48:49]
	v_and_b32_e32 v82, 0xff, v92
	v_lshlrev_b32_e32 v82, 4, v82
	v_add_u32_e32 v82, 0x21400, v82
	ds_read_b128 v[82:85], v82
	v_lshlrev_b64 v[94:95], 5, v[92:93]
	s_waitcnt lgkmcnt(0)
	v_mov_b32_e32 v86, v83
	v_mov_b32_e32 v87, v84
	v_mov_b32_e32 v83, v85
	v_pk_add_f32 v[82:83], v[86:87], v[82:83]
	s_nop 0
	v_add_f32_e32 v0, v82, v83
	v_add_f32_e32 v0, 0, v0
	v_fmamk_f32 v0, v0, 0x3a800000, v212
	v_mul_f32_e32 v82, 0x4b800000, v0
	v_cmp_gt_f32_e64 s[50:51], s69, v0
	s_nop 1
	v_cndmask_b32_e64 v0, v0, v82, s[50:51]
	v_rsq_f32_e32 v0, v0
	s_nop 0
	v_mul_f32_e32 v82, 0x45800000, v0
	v_cndmask_b32_e64 v86, v0, v82, s[50:51]
	v_pk_mul_f32 v[80:81], v[80:81], v[86:87] op_sel_hi:[1,0]
	v_pk_mul_f32 v[78:79], v[78:79], v[86:87] op_sel_hi:[1,0]
	v_pk_mul_f32 v[76:77], v[76:77], v[86:87] op_sel_hi:[1,0]
	v_pk_mul_f32 v[74:75], v[74:75], v[86:87] op_sel_hi:[1,0]
	s_cbranch_vccnz .LBB0_194
	v_mul_f32_e32 v0, v79, v79
	v_mul_f32_e32 v82, v81, v81
	v_fmac_f32_e32 v0, v78, v78
	v_fmac_f32_e32 v82, v80, v80
	v_add_f32_e32 v0, v0, v82
	v_mul_f32_e32 v82, v75, v75
	v_fmac_f32_e32 v82, v74, v74
	v_add_f32_e32 v0, v82, v0
	v_mul_f32_e32 v82, v77, v77
	v_fmac_f32_e32 v82, v76, v76
	v_and_b32_e32 v83, 64, v213
	v_add_f32_e32 v0, v82, v0
	v_xor_b32_e32 v82, 16, v213
	v_add_u32_e32 v83, 64, v83
	v_cmp_lt_i32_e32 vcc, v82, v83
	s_nop 1
	v_cndmask_b32_e32 v82, v213, v82, vcc
	v_lshlrev_b32_e32 v82, 2, v82
	ds_bpermute_b32 v82, v82, v0
	s_waitcnt lgkmcnt(0)
	v_add_f32_e32 v0, v0, v82
	v_xor_b32_e32 v82, 32, v213
	v_cmp_lt_i32_e32 vcc, v82, v83
	s_nop 1
	v_cndmask_b32_e32 v82, v213, v82, vcc
	v_lshlrev_b32_e32 v82, 2, v82
	ds_bpermute_b32 v82, v82, v0
	s_and_saveexec_b64 s[16:17], s[38:39]
	s_cbranch_execz .LBB0_193
	v_lshlrev_b64 v[84:85], 2, v[92:93]
	v_lshl_add_u64 v[88:89], s[78:79], 0, v[94:95]
	v_lshl_add_u64 v[84:85], v[84:85], 2, s[88:89]
	v_cndmask_b32_e64 v85, v85, v89, s[42:43]
	v_cndmask_b32_e64 v84, v84, v88, s[42:43]
	s_lshl_b32 s72, s4, 2
	v_lshl_add_u64 v[84:85], v[84:85], 0, s[72:73]
	s_waitcnt lgkmcnt(0)
	v_add_f32_e32 v0, v0, v82
	global_store_dword v[84:85], v0, off

; __device__ __forceinline__ unsigned cvtpk(float lo, float hi) { f32x2 v = {lo, hi}; bf16x2_t b = __builtin_convertvector(v, bf16x2_t); return __builtin_bit_cast(unsigned, b); }
;     __device__ __forceinline__ void operator()(AccRef acc, const Unit& u, int wr, int wc, int fr, int fq) const {
;     ...
;                 const int row = row0 + ai * 128 + m * 16;
;                 const float rs = rsqrtf(ssq_sum<4>(ssqx + (size_t)row * 4) * (1.0f / DM) + EPS);
;                 bf16_t* rowp = O + (size_t)row * NPROJ + col0;
; #pragma unroll
;                 for (int bj = 0; bj < 2; ++bj) {
;                     f32x4 v0 = acc[ai][bj][m][0] * rs, v1 = acc[ai][bj][m][1] * rs;
;                     if (u.pn == 6 || (u.pn == 7 && bj == 0)) {
;                         float s = (v0[0] * v0[0] + v0[1] * v0[1]) + (v0[2] * v0[2] + v0[3] * v0[3]) + (v1[0] * v1[0] + v1[1] * v1[1]) + (v1[2] * v1[2] + v1[3] * v1[3]);
;                         s += __shfl_xor(s, 16); s += __shfl_xor(s, 32);
;                         if (fq == 0) { if (u.pn == 6) ssqq[(size_t)row * 8 + bj * 4 + wc] = s; else ssqkv[(size_t)row * 4 + wc] = s; }
;                     }
;                     if (u.pn == 7 && bj == 1 && wc == 0) { const int pos = row & (SEQ - 1); rope8(v0, v1, cost + pos * 16, sint + pos * 16, fq); }
;                     u32x4 w; w.x = cvtpk(v0[0], v0[1]); w.y = cvtpk(v0[2], v0[3]); w.z = cvtpk(v1[0], v1[1]); w.w = cvtpk(v1[2], v1[3]);
;                     st16_wt(rowp + bj * 128, w);
.LBB0_198:
	s_waitcnt lgkmcnt(0)
	v_cvt_pk_bf16_f32 v66, v90, v91
	v_cvt_pk_bf16_f32 v67, v84, v85
	v_cvt_pk_bf16_f32 v68, v86, v87
	v_cvt_pk_bf16_f32 v69, v88, v89
	v_add_u32_e32 v76, 0x80, v148
	global_store_dwordx4 v[82:83], v[66:69], off offset:256
	v_ashrrev_i32_e32 v77, 31, v76
	s_and_b64 vcc, exec, s[48:49]
	v_and_b32_e32 v66, 0xff, v76
	v_lshlrev_b32_e32 v66, 4, v66
	v_add_u32_e32 v66, 0x21400, v66
	ds_read_b128 v[66:69], v66
	v_lshlrev_b64 v[78:79], 5, v[76:77]
	s_waitcnt lgkmcnt(0)
	v_mov_b32_e32 v70, v67
	v_mov_b32_e32 v71, v68
	v_mov_b32_e32 v67, v69
	v_pk_add_f32 v[66:67], v[70:71], v[66:67]
	s_nop 0
	v_add_f32_e32 v0, v66, v67
	v_add_f32_e32 v0, 0, v0
	v_fmamk_f32 v0, v0, 0x3a800000, v212
	v_mul_f32_e32 v66, 0x4b800000, v0
	v_cmp_gt_f32_e64 s[50:51], s69, v0
	s_nop 1
	v_cndmask_b32_e64 v0, v0, v66, s[50:51]
	v_rsq_f32_e32 v0, v0
	s_nop 0
	v_mul_f32_e32 v66, 0x45800000, v0
	v_cndmask_b32_e64 v70, v0, v66, s[50:51]
	v_pk_mul_f32 v[64:65], v[64:65], v[70:71] op_sel_hi:[1,0]
	v_pk_mul_f32 v[62:63], v[62:63], v[70:71] op_sel_hi:[1,0]
	v_pk_mul_f32 v[60:61], v[60:61], v[70:71] op_sel_hi:[1,0]
	v_pk_mul_f32 v[58:59], v[58:59], v[70:71] op_sel_hi:[1,0]
	s_cbranch_vccnz .LBB0_202
	v_mul_f32_e32 v0, v63, v63
	v_mul_f32_e32 v66, v65, v65
	v_fmac_f32_e32 v0, v62, v62
	v_fmac_f32_e32 v66, v64, v64
	v_add_f32_e32 v0, v0, v66
	v_mul_f32_e32 v66, v59, v59
	v_fmac_f32_e32 v66, v58, v58
	v_add_f32_e32 v0, v66, v0
	v_mul_f32_e32 v66, v61, v61
	v_fmac_f32_e32 v66, v60, v60
	v_and_b32_e32 v67, 64, v213
	v_add_f32_e32 v0, v66, v0
	v_xor_b32_e32 v66, 16, v213
	v_add_u32_e32 v67, 64, v67
	v_cmp_lt_i32_e32 vcc, v66, v67
	s_nop 1
	v_cndmask_b32_e32 v66, v213, v66, vcc
	v_lshlrev_b32_e32 v66, 2, v66
	ds_bpermute_b32 v66, v66, v0
	s_waitcnt lgkmcnt(0)
	v_add_f32_e32 v0, v0, v66
	v_xor_b32_e32 v66, 32, v213
	v_cmp_lt_i32_e32 vcc, v66, v67
	s_nop 1
	v_cndmask_b32_e32 v66, v213, v66, vcc
	v_lshlrev_b32_e32 v66, 2, v66
	ds_bpermute_b32 v66, v66, v0
	s_and_saveexec_b64 s[16:17], s[38:39]
	s_cbranch_execz .LBB0_201
	v_lshlrev_b64 v[68:69], 2, v[76:77]
	v_lshl_add_u64 v[72:73], s[78:79], 0, v[78:79]
	v_lshl_add_u64 v[68:69], v[68:69], 2, s[88:89]
	v_cndmask_b32_e64 v69, v69, v73, s[42:43]
	v_cndmask_b32_e64 v68, v68, v72, s[42:43]
	s_lshl_b32 s72, s4, 2
	v_lshl_add_u64 v[68:69], v[68:69], 0, s[72:73]
	s_waitcnt lgkmcnt(0)
	v_add_f32_e32 v0, v0, v66
	global_store_dword v[68:69], v0, off

; __device__ __forceinline__ unsigned cvtpk(float lo, float hi) { f32x2 v = {lo, hi}; bf16x2_t b = __builtin_convertvector(v, bf16x2_t); return __builtin_bit_cast(unsigned, b); }
;     __device__ __forceinline__ void operator()(AccRef acc, const Unit& u, int wr, int wc, int fr, int fq) const {
;     ...
;                 const int row = row0 + ai * 128 + m * 16;
;                 const float rs = rsqrtf(ssq_sum<4>(ssqx + (size_t)row * 4) * (1.0f / DM) + EPS);
;                 bf16_t* rowp = O + (size_t)row * NPROJ + col0;
; #pragma unroll
;                 for (int bj = 0; bj < 2; ++bj) {
;                     f32x4 v0 = acc[ai][bj][m][0] * rs, v1 = acc[ai][bj][m][1] * rs;
;                     if (u.pn == 6 || (u.pn == 7 && bj == 0)) {
;                         float s = (v0[0] * v0[0] + v0[1] * v0[1]) + (v0[2] * v0[2] + v0[3] * v0[3]) + (v1[0] * v1[0] + v1[1] * v1[1]) + (v1[2] * v1[2] + v1[3] * v1[3]);
;                         s += __shfl_xor(s, 16); s += __shfl_xor(s, 32);
;                         if (fq == 0) { if (u.pn == 6) ssqq[(size_t)row * 8 + bj * 4 + wc] = s; else ssqkv[(size_t)row * 4 + wc] = s; }
;                     }
;                     if (u.pn == 7 && bj == 1 && wc == 0) { const int pos = row & (SEQ - 1); rope8(v0, v1, cost + pos * 16, sint + pos * 16, fq); }
;                     u32x4 w; w.x = cvtpk(v0[0], v0[1]); w.y = cvtpk(v0[2], v0[3]); w.z = cvtpk(v1[0], v1[1]); w.w = cvtpk(v1[2], v1[3]);
;                     st16_wt(rowp + bj * 128, w);
.LBB0_206:
	s_waitcnt lgkmcnt(0)
	v_cvt_pk_bf16_f32 v50, v74, v75
	v_cvt_pk_bf16_f32 v51, v68, v69
	v_cvt_pk_bf16_f32 v52, v70, v71
	v_cvt_pk_bf16_f32 v53, v72, v73
	v_add_u32_e32 v60, 0x90, v148
	global_store_dwordx4 v[66:67], v[50:53], off offset:256
	v_ashrrev_i32_e32 v61, 31, v60
	s_and_b64 vcc, exec, s[48:49]
	v_and_b32_e32 v50, 0xff, v60
	v_lshlrev_b32_e32 v50, 4, v50
	v_add_u32_e32 v50, 0x21400, v50
	ds_read_b128 v[50:53], v50
	v_lshlrev_b64 v[62:63], 5, v[60:61]
	s_waitcnt lgkmcnt(0)
	v_mov_b32_e32 v54, v51
	v_mov_b32_e32 v55, v52
	v_mov_b32_e32 v51, v53
	v_pk_add_f32 v[50:51], v[54:55], v[50:51]
	s_nop 0
	v_add_f32_e32 v0, v50, v51
	v_add_f32_e32 v0, 0, v0
	v_fmamk_f32 v0, v0, 0x3a800000, v212
	v_mul_f32_e32 v50, 0x4b800000, v0
	v_cmp_gt_f32_e64 s[50:51], s69, v0
	s_nop 1
	v_cndmask_b32_e64 v0, v0, v50, s[50:51]
	v_rsq_f32_e32 v0, v0
	s_nop 0
	v_mul_f32_e32 v50, 0x45800000, v0
	v_cndmask_b32_e64 v54, v0, v50, s[50:51]
	v_pk_mul_f32 v[48:49], v[48:49], v[54:55] op_sel_hi:[1,0]
	v_pk_mul_f32 v[46:47], v[46:47], v[54:55] op_sel_hi:[1,0]
	v_pk_mul_f32 v[44:45], v[44:45], v[54:55] op_sel_hi:[1,0]
	v_pk_mul_f32 v[42:43], v[42:43], v[54:55] op_sel_hi:[1,0]
	s_cbranch_vccnz .LBB0_210
	v_mul_f32_e32 v0, v47, v47
	v_mul_f32_e32 v50, v49, v49
	v_fmac_f32_e32 v0, v46, v46
	v_fmac_f32_e32 v50, v48, v48
	v_add_f32_e32 v0, v0, v50
	v_mul_f32_e32 v50, v43, v43
	v_fmac_f32_e32 v50, v42, v42
	v_add_f32_e32 v0, v50, v0
	v_mul_f32_e32 v50, v45, v45
	v_fmac_f32_e32 v50, v44, v44
	v_and_b32_e32 v51, 64, v213
	v_add_f32_e32 v0, v50, v0
	v_xor_b32_e32 v50, 16, v213
	v_add_u32_e32 v51, 64, v51
	v_cmp_lt_i32_e32 vcc, v50, v51
	s_nop 1
	v_cndmask_b32_e32 v50, v213, v50, vcc
	v_lshlrev_b32_e32 v50, 2, v50
	ds_bpermute_b32 v50, v50, v0
	s_waitcnt lgkmcnt(0)
	v_add_f32_e32 v0, v0, v50
	v_xor_b32_e32 v50, 32, v213
	v_cmp_lt_i32_e32 vcc, v50, v51
	s_nop 1
	v_cndmask_b32_e32 v50, v213, v50, vcc
	v_lshlrev_b32_e32 v50, 2, v50
	ds_bpermute_b32 v50, v50, v0
	s_and_saveexec_b64 s[16:17], s[38:39]
	s_cbranch_execz .LBB0_209
	v_lshlrev_b64 v[52:53], 2, v[60:61]
	v_lshl_add_u64 v[56:57], s[78:79], 0, v[62:63]
	v_lshl_add_u64 v[52:53], v[52:53], 2, s[88:89]
	v_cndmask_b32_e64 v53, v53, v57, s[42:43]
	v_cndmask_b32_e64 v52, v52, v56, s[42:43]
	s_lshl_b32 s72, s4, 2
	v_lshl_add_u64 v[52:53], v[52:53], 0, s[72:73]
	s_waitcnt lgkmcnt(0)
	v_add_f32_e32 v0, v0, v50
	global_store_dword v[52:53], v0, off

;     __device__ __forceinline__ void operator()(AccRef acc, const Unit& u, int wr, int wc, int fr, int fq) const {
;     ...
;                 const int row = row0 + ai * 128 + m * 16;
;                 const float rs = rsqrtf(ssq_sum<4>(ssqx + (size_t)row * 4) * (1.0f / DM) + EPS);
;                 bf16_t* rowp = O + (size_t)row * NPROJ + col0;
; #pragma unroll
;                 for (int bj = 0; bj < 2; ++bj) {
;                     f32x4 v0 = acc[ai][bj][m][0] * rs, v1 = acc[ai][bj][m][1] * rs;
;                     if (u.pn == 6 || (u.pn == 7 && bj == 0)) {
;                         float s = (v0[0] * v0[0] + v0[1] * v0[1]) + (v0[2] * v0[2] + v0[3] * v0[3]) + (v1[0] * v1[0] + v1[1] * v1[1]) + (v1[2] * v1[2] + v1[3] * v1[3]);
;                         s += __shfl_xor(s, 16); s += __shfl_xor(s, 32);
;                         if (fq == 0) { if (u.pn == 6) ssqq[(size_t)row * 8 + bj * 4 + wc] = s; else ssqkv[(size_t)row * 4 + wc] = s; }
;                     }
.LBB0_214:
	s_waitcnt lgkmcnt(0)
	v_cvt_pk_bf16_f32 v34, v58, v59
	v_cvt_pk_bf16_f32 v35, v52, v53
	v_cvt_pk_bf16_f32 v36, v54, v55
	v_cvt_pk_bf16_f32 v37, v56, v57
	v_add_u32_e32 v44, 0xa0, v148
	global_store_dwordx4 v[50:51], v[34:37], off offset:256
	v_ashrrev_i32_e32 v45, 31, v44
	s_and_b64 vcc, exec, s[48:49]
	v_and_b32_e32 v34, 0xff, v44
	v_lshlrev_b32_e32 v34, 4, v34
	v_add_u32_e32 v34, 0x21400, v34
	ds_read_b128 v[34:37], v34
	v_lshlrev_b64 v[46:47], 5, v[44:45]
	s_waitcnt lgkmcnt(0)
	v_mov_b32_e32 v38, v35
	v_mov_b32_e32 v39, v36
	v_mov_b32_e32 v35, v37
	v_pk_add_f32 v[34:35], v[38:39], v[34:35]
	s_nop 0
	v_add_f32_e32 v0, v34, v35
	v_add_f32_e32 v0, 0, v0
	v_fmamk_f32 v0, v0, 0x3a800000, v212
	v_mul_f32_e32 v34, 0x4b800000, v0
	v_cmp_gt_f32_e64 s[50:51], s69, v0
	s_nop 1
	v_cndmask_b32_e64 v0, v0, v34, s[50:51]
	v_rsq_f32_e32 v0, v0
	s_nop 0
	v_mul_f32_e32 v34, 0x45800000, v0
	v_cndmask_b32_e64 v38, v0, v34, s[50:51]
	v_pk_mul_f32 v[32:33], v[32:33], v[38:39] op_sel_hi:[1,0]
	v_pk_mul_f32 v[30:31], v[30:31], v[38:39] op_sel_hi:[1,0]
	v_pk_mul_f32 v[28:29], v[28:29], v[38:39] op_sel_hi:[1,0]
	v_pk_mul_f32 v[26:27], v[26:27], v[38:39] op_sel_hi:[1,0]
	s_cbranch_vccnz .LBB0_218
	v_mul_f32_e32 v0, v31, v31
	v_mul_f32_e32 v34, v33, v33
	v_fmac_f32_e32 v0, v30, v30
	v_fmac_f32_e32 v34, v32, v32
	v_add_f32_e32 v0, v0, v34
	v_mul_f32_e32 v34, v27, v27
	v_fmac_f32_e32 v34, v26, v26
	v_add_f32_e32 v0, v34, v0
	v_mul_f32_e32 v34, v29, v29
	v_fmac_f32_e32 v34, v28, v28
	v_and_b32_e32 v35, 64, v213
	v_add_f32_e32 v0, v34, v0
	v_xor_b32_e32 v34, 16, v213
	v_add_u32_e32 v35, 64, v35
	v_cmp_lt_i32_e32 vcc, v34, v35
	s_nop 1
	v_cndmask_b32_e32 v34, v213, v34, vcc
	v_lshlrev_b32_e32 v34, 2, v34
	ds_bpermute_b32 v34, v34, v0
	s_waitcnt lgkmcnt(0)
	v_add_f32_e32 v0, v0, v34
	v_xor_b32_e32 v34, 32, v213
	v_cmp_lt_i32_e32 vcc, v34, v35
	s_nop 1
	v_cndmask_b32_e32 v34, v213, v34, vcc
	v_lshlrev_b32_e32 v34, 2, v34
	ds_bpermute_b32 v34, v34, v0
	s_and_saveexec_b64 s[16:17], s[38:39]
	s_cbranch_execz .LBB0_217
	v_lshlrev_b64 v[36:37], 2, v[44:45]
	v_lshl_add_u64 v[40:41], s[78:79], 0, v[46:47]
	v_lshl_add_u64 v[36:37], v[36:37], 2, s[88:89]
	v_cndmask_b32_e64 v37, v37, v41, s[42:43]
	v_cndmask_b32_e64 v36, v36, v40, s[42:43]
	s_lshl_b32 s72, s4, 2
	v_lshl_add_u64 v[36:37], v[36:37], 0, s[72:73]
	s_waitcnt lgkmcnt(0)
	v_add_f32_e32 v0, v0, v34
	global_store_dword v[36:37], v0, off

;     __device__ __forceinline__ void operator()(AccRef acc, const Unit& u, int wr, int wc, int fr, int fq) const {
;     ...
;                 const int row = row0 + ai * 128 + m * 16;
;                 const float rs = rsqrtf(ssq_sum<4>(ssqx + (size_t)row * 4) * (1.0f / DM) + EPS);
;                 bf16_t* rowp = O + (size_t)row * NPROJ + col0;
; #pragma unroll
;                 for (int bj = 0; bj < 2; ++bj) {
;                     f32x4 v0 = acc[ai][bj][m][0] * rs, v1 = acc[ai][bj][m][1] * rs;
;                     if (u.pn == 6 || (u.pn == 7 && bj == 0)) {
;                         float s = (v0[0] * v0[0] + v0[1] * v0[1]) + (v0[2] * v0[2] + v0[3] * v0[3]) + (v1[0] * v1[0] + v1[1] * v1[1]) + (v1[2] * v1[2] + v1[3] * v1[3]);
;                         s += __shfl_xor(s, 16); s += __shfl_xor(s, 32);
;                         if (fq == 0) { if (u.pn == 6) ssqq[(size_t)row * 8 + bj * 4 + wc] = s; else ssqkv[(size_t)row * 4 + wc] = s; }
;                     }
.LBB0_222:
	s_waitcnt lgkmcnt(0)
	v_cvt_pk_bf16_f32 v18, v42, v43
	v_cvt_pk_bf16_f32 v19, v36, v37
	v_cvt_pk_bf16_f32 v20, v38, v39
	v_cvt_pk_bf16_f32 v21, v40, v41
	v_add_u32_e32 v28, 0xb0, v148
	global_store_dwordx4 v[34:35], v[18:21], off offset:256
	v_ashrrev_i32_e32 v29, 31, v28
	s_and_b64 vcc, exec, s[48:49]
	v_and_b32_e32 v18, 0xff, v28
	v_lshlrev_b32_e32 v18, 4, v18
	v_add_u32_e32 v18, 0x21400, v18
	ds_read_b128 v[18:21], v18
	v_lshlrev_b64 v[30:31], 5, v[28:29]
	s_waitcnt lgkmcnt(0)
	v_mov_b32_e32 v22, v19
	v_mov_b32_e32 v23, v20
	v_mov_b32_e32 v19, v21
	v_pk_add_f32 v[18:19], v[22:23], v[18:19]
	s_nop 0
	v_add_f32_e32 v0, v18, v19
	v_add_f32_e32 v0, 0, v0
	v_fmamk_f32 v0, v0, 0x3a800000, v212
	v_mul_f32_e32 v18, 0x4b800000, v0
	v_cmp_gt_f32_e64 s[50:51], s69, v0
	s_nop 1
	v_cndmask_b32_e64 v0, v0, v18, s[50:51]
	v_rsq_f32_e32 v0, v0
	s_nop 0
	v_mul_f32_e32 v18, 0x45800000, v0
	v_cndmask_b32_e64 v22, v0, v18, s[50:51]
	v_pk_mul_f32 v[16:17], v[16:17], v[22:23] op_sel_hi:[1,0]
	v_pk_mul_f32 v[14:15], v[14:15], v[22:23] op_sel_hi:[1,0]
	v_pk_mul_f32 v[12:13], v[12:13], v[22:23] op_sel_hi:[1,0]
	v_pk_mul_f32 v[10:11], v[10:11], v[22:23] op_sel_hi:[1,0]
	s_cbranch_vccnz .LBB0_226
	v_mul_f32_e32 v0, v15, v15
	v_mul_f32_e32 v18, v17, v17
	v_fmac_f32_e32 v0, v14, v14
	v_fmac_f32_e32 v18, v16, v16
	v_add_f32_e32 v0, v0, v18
	v_mul_f32_e32 v18, v11, v11
	v_fmac_f32_e32 v18, v10, v10
	v_add_f32_e32 v0, v18, v0
	v_mul_f32_e32 v18, v13, v13
	v_fmac_f32_e32 v18, v12, v12
	v_and_b32_e32 v19, 64, v213
	v_add_f32_e32 v0, v18, v0
	v_xor_b32_e32 v18, 16, v213
	v_add_u32_e32 v19, 64, v19
	v_cmp_lt_i32_e32 vcc, v18, v19
	s_nop 1
	v_cndmask_b32_e32 v18, v213, v18, vcc
	v_lshlrev_b32_e32 v18, 2, v18
	ds_bpermute_b32 v18, v18, v0
	s_waitcnt lgkmcnt(0)
	v_add_f32_e32 v0, v0, v18
	v_xor_b32_e32 v18, 32, v213
	v_cmp_lt_i32_e32 vcc, v18, v19
	s_nop 1
	v_cndmask_b32_e32 v18, v213, v18, vcc
	v_lshlrev_b32_e32 v18, 2, v18
	ds_bpermute_b32 v18, v18, v0
	s_and_saveexec_b64 s[16:17], s[38:39]
	s_cbranch_execz .LBB0_225
	v_lshlrev_b64 v[20:21], 2, v[28:29]
	v_lshl_add_u64 v[24:25], s[78:79], 0, v[30:31]
	v_lshl_add_u64 v[20:21], v[20:21], 2, s[88:89]
	v_cndmask_b32_e64 v21, v21, v25, s[42:43]
	v_cndmask_b32_e64 v20, v20, v24, s[42:43]
	s_lshl_b32 s72, s4, 2
	v_lshl_add_u64 v[20:21], v[20:21], 0, s[72:73]
	s_waitcnt lgkmcnt(0)
	v_add_f32_e32 v0, v0, v18
	global_store_dword v[20:21], v0, off
